# hg<true>: DPP 8-lane sum instead of 3 bpermutes; score tile computed transposed -> 4 ds_write_b64 instead of 16 b16
# speedup vs baseline: 1.0153x; 1.0054x over previous
; #define LAS __attribute__((address_space(3)))
; __device__ __forceinline__ unsigned pk2(float lo, float hi) { typedef float f2v __attribute__((ext_vector_type(2))); typedef __bf16 b2v __attribute__((ext_vector_type(2))); const f2v v = {lo, hi}; const b2v b = __builtin_convertvector(v, b2v); return __builtin_bit_cast(unsigned, b); }
; #define lane lane_id()
; template <bool FULL, bool STORE = true>
; __device__ __forceinline__ void hg_item(const Prm& P, LAS unsigned char* lds, int item, int wave) {
;     unsigned char* ws = P.ws; const int lane = lane_id(), tid = wave * 64 + lane;
;     const int b = item >> 6, h = (item >> 3) & 7, seg = item & 7;
;     const int l31 = lane & 31, lh = lane >> 5;
;     const int k2 = lane * 2, tg = wave;
;     const int kb = wave >> 1, vb0 = (wave & 1) * 2;
;     const _Float16* LF = (const _Float16*)P.out; const bf16_t* Q = (const bf16_t*)(ws + WS_Q); const bf16_t* IV = (const bf16_t*)(ws + WS_IV); const bf16_t* GH = (const bf16_t*)(ws + WS_GH);
;     bf16_t* AHG = (bf16_t*)(ws + WS_AHG);
;     float* AGG = (float*)(ws + WS_HGAGG); float* DEC = (float*)(ws + WS_HGDEC);
;     f32x16 S[2];
; #pragma unroll
;     for (int i = 0; i < 2; ++i)
; #pragma unroll
;         for (int r = 0; r < 16; ++r) S[i][r] = 0.f;
;     float sumlog0 = 0.f, sumlog1 = 0.f;
;     if (FULL) {
;         for (int s2 = 0; s2 < seg; ++s2) { const int it2 = item - seg + s2;
; #pragma unroll
;             for (int g4 = 0; g4 < 4; ++g4) { const f32x4 d = *(const f32x4*)(DEC + it2 * 128 + kb * 32 + 8 * g4 + 4 * lh);
; #pragma unroll
;                 for (int i = 0; i < 2; ++i)
; #pragma unroll
;                     for (int j = 0; j < 4; ++j) { const int r = 4 * g4 + j; S[i][r] = d[j] * S[i][r] + AGG[(size_t)((it2 * 8 + wave) * 2 + i) * 1024 + r * 64 + lane]; } } }
; #pragma unroll
;         for (int i = 0; i < 2; ++i)
; #pragma unroll
;             for (int g4 = 0; g4 < 4; ++g4) { u32x2 w; w.x = pk2(S[i][4 * g4], S[i][4 * g4 + 1]); w.y = pk2(S[i][4 * g4 + 2], S[i][4 * g4 + 3]);
;                 *(LAS u32x2*)(lds + HL_ST + ((vb0 + i) * 32 + l31) * 272 + (kb * 32 + 8 * g4 + 4 * lh) * 2) = w; }
;         for (int e = tid; e < 32 * 16; e += NTHR) { const int t = e >> 4, c = e & 15; *(LAS unsigned*)(lds + HL_PP + t * 144 + 64 + c * 4) = 0u; }
;     }
;     float c0[8], c1[8]; unsigned qw[8], ivw[8]; u32x4 ghw0, ghw1;
;     ...
;     HG_LOADS(0);
.LBB0_838:
	s_or_b64 exec, exec, s[18:19]
	s_ashr_i32 s84, s91, 6
	s_and_b32 s18, s2, 7
	s_ashr_i32 s85, s84, 31
	s_lshl_b32 s33, s18, 21
	s_lshl_b32 s19, s54, 1
	s_lshl_b32 s87, s18, 10
	s_lshl_b64 s[52:53], s[84:85], 13
	s_lshl_b32 s18, s26, 10
	s_and_b32 s86, s19, 0x700
	s_or_b32 s18, s52, s18
	s_add_u32 s20, s18, s55
	v_lshlrev_b32_e32 v36, 1, v32
	s_addc_u32 s21, s53, 0
	s_lshl_b32 s22, s91, 4
	s_and_b32 s74, s22, 0x380
	v_ashrrev_i32_e32 v37, 31, v36
	v_lshl_add_u64 v[76:77], v[36:37], 0, s[74:75]
	s_lshl_b64 s[20:21], s[20:21], 10
	v_lshl_add_u64 v[44:45], v[76:77], 0, s[20:21]
	v_lshlrev_b64 v[44:45], 1, v[44:45]
	v_lshl_add_u64 v[46:47], s[70:71], 0, v[44:45]
	global_load_dword v240, v[46:47], off nt
	v_lshl_add_u64 v[48:49], s[62:63], 0, v[44:45]
	global_load_dword v110, v[48:49], off nt
	v_lshl_add_u64 v[48:49], s[64:65], 0, v[44:45]
	s_mov_b64 s[20:21], 0x800
	v_ashrrev_i32_e32 v38, 3, v38
	s_mov_b32 s19, s53
	v_lshlrev_b32_e32 v43, 4, v32
	v_and_b32_e32 v94, 0x70, v43
	v_lshlrev_b32_e32 v74, 1, v94
	v_and_b32_e32 v60, 64, v108
	v_xor_b32_e32 v59, 1, v108
	v_add_u32_e32 v60, 64, v60
	v_cmp_lt_i32_e32 vcc, v59, v60
	v_lshlrev_b32_e32 v128, 4, v40
	v_readlane_b32 s46, v255, 48
	v_cndmask_b32_e32 v59, v108, v59, vcc
	v_lshlrev_b32_e32 v129, 2, v59
	v_xor_b32_e32 v59, 2, v108
	v_cmp_lt_i32_e32 vcc, v59, v60
	v_readlane_b32 s22, v255, 37
	v_readlane_b32 s24, v255, 38
	v_cndmask_b32_e32 v59, v108, v59, vcc
	v_lshlrev_b32_e32 v130, 2, v59
	v_xor_b32_e32 v59, 4, v108
	v_cmp_lt_i32_e32 vcc, v59, v60
	v_readlane_b32 s26, v255, 39
	v_readlane_b32 s28, v255, 40
	v_cndmask_b32_e32 v59, v108, v59, vcc
	v_readlane_b32 s30, v255, 41
	v_readlane_b32 s34, v255, 42
	v_readlane_b32 s36, v255, 43
	v_readlane_b32 s38, v255, 44
	v_readlane_b32 s40, v255, 45
	v_readlane_b32 s42, v255, 46
	v_readlane_b32 s44, v255, 47
	v_add_u32_e32 v96, s46, v34
	v_readlane_b32 s48, v255, 49
	v_readlane_b32 s50, v255, 50
	v_add_u32_e32 v61, s97, v34
	v_add_u32_e32 v63, s22, v34
	v_add_u32_e32 v64, s24, v34
	v_add_u32_e32 v65, s26, v34
	v_add_u32_e32 v66, s28, v34
	v_add_u32_e32 v67, s30, v34
	v_add_u32_e32 v68, s34, v34
	v_add_u32_e32 v69, s36, v34
	v_add_u32_e32 v70, s38, v34
	v_add_u32_e32 v71, s40, v34
	v_add_u32_e32 v72, s42, v34
	v_add_u32_e32 v73, s44, v34
	v_mul_lo_u32 v102, v96, s72
	v_lshlrev_b32_e32 v131, 2, v59
	v_or_b32_e32 v59, s97, v42
	v_lshlrev_b32_e32 v126, 3, v32
	v_mul_lo_u32 v58, v38, s94
	v_mul_u32_u24_e32 v41, 0x110, v33
	v_add_u32_e32 v58, 0, v58
	v_mad_u32_u24 v59, v59, s3, 0
	v_add_u32_e32 v133, v59, v128
	v_add_u32_e32 v156, v35, v41
	global_load_dword v111, v[48:49], off nt
	global_load_dword v241, v[46:47], off offset:2048 nt
	v_lshl_add_u64 v[46:47], v[44:45], 0, s[20:21]
	v_lshl_add_u64 v[48:49], s[62:63], 0, v[46:47]
	v_lshl_add_u64 v[46:47], s[64:65], 0, v[46:47]
	s_mov_b64 s[20:21], 0x1000
	global_load_dword v112, v[48:49], off nt
	global_load_dword v113, v[46:47], off nt
	v_lshl_add_u64 v[46:47], v[44:45], 0, s[20:21]
	v_lshl_add_u64 v[48:49], s[70:71], 0, v[46:47]
	s_mov_b64 s[20:21], 0x1800
	global_load_dword v242, v[48:49], off nt
	v_lshl_add_u64 v[48:49], s[62:63], 0, v[46:47]
	v_lshl_add_u64 v[46:47], s[64:65], 0, v[46:47]
	global_load_dword v114, v[48:49], off nt
	global_load_dword v115, v[46:47], off nt
	v_lshl_add_u64 v[46:47], v[44:45], 0, s[20:21]
	v_lshl_add_u64 v[48:49], s[70:71], 0, v[46:47]
	s_mov_b64 s[20:21], 0x2000
	global_load_dword v243, v[48:49], off nt
	v_lshl_add_u64 v[48:49], s[62:63], 0, v[46:47]
	v_lshl_add_u64 v[46:47], s[64:65], 0, v[46:47]
	global_load_dword v116, v[48:49], off nt
	global_load_dword v117, v[46:47], off nt
	v_lshl_add_u64 v[46:47], v[44:45], 0, s[20:21]
	v_lshl_add_u64 v[48:49], s[70:71], 0, v[46:47]
	s_mov_b64 s[20:21], 0x2800
	global_load_dword v244, v[48:49], off nt
	v_lshl_add_u64 v[48:49], s[62:63], 0, v[46:47]
	v_lshl_add_u64 v[46:47], s[64:65], 0, v[46:47]
	global_load_dword v118, v[48:49], off nt
	global_load_dword v119, v[46:47], off nt
	v_lshl_add_u64 v[46:47], v[44:45], 0, s[20:21]
	v_lshl_add_u64 v[48:49], s[70:71], 0, v[46:47]
	s_mov_b64 s[20:21], 0x3000
	global_load_dword v245, v[48:49], off nt
	v_lshl_add_u64 v[48:49], s[62:63], 0, v[46:47]
	v_lshl_add_u64 v[46:47], s[64:65], 0, v[46:47]
	global_load_dword v120, v[48:49], off nt
	global_load_dword v121, v[46:47], off nt
	v_lshl_add_u64 v[46:47], v[44:45], 0, s[20:21]
	v_lshl_add_u64 v[48:49], s[70:71], 0, v[46:47]
	s_mov_b64 s[20:21], 0x3800
	v_lshl_add_u64 v[44:45], v[44:45], 0, s[20:21]
	v_readlane_b32 s20, v255, 36
	global_load_dword v246, v[48:49], off nt
	v_lshl_add_u64 v[48:49], s[62:63], 0, v[46:47]
	v_lshl_add_u64 v[46:47], s[64:65], 0, v[46:47]
	global_load_dword v122, v[48:49], off nt
	global_load_dword v123, v[46:47], off nt
	v_lshl_add_u64 v[46:47], s[70:71], 0, v[44:45]
	v_add_u32_e32 v62, s20, v34
	global_load_dword v247, v[46:47], off nt
	v_lshl_add_u64 v[46:47], s[62:63], 0, v[44:45]
	v_lshl_add_u64 v[44:45], s[64:65], 0, v[44:45]
	global_load_dword v124, v[46:47], off nt
	global_load_dword v125, v[44:45], off nt
	v_lshlrev_b32_e32 v47, 2, v32
	v_ashrrev_i32_e32 v39, 31, v38
	v_lshl_add_u64 v[44:45], s[18:19], 0, v[38:39]
	v_lshlrev_b64 v[44:45], 11, v[44:45]
	v_lshl_add_u64 v[44:45], s[66:67], 0, v[44:45]
	s_lshl_b32 s18, s74, 1
	s_mov_b32 s19, s75
	v_lshl_add_u64 v[44:45], v[44:45], 0, s[18:19]
	v_lshl_add_u64 v[44:45], v[44:45], 0, v[74:75]
	global_load_dwordx4 v[48:51], v[44:45], off offset:16 nt
	global_load_dwordx4 v[52:55], v[44:45], off nt
	s_movk_i32 s18, 0x120
	v_mul_lo_u32 v127, v32, s18
	v_readlane_b32 s18, v255, 32
	s_add_i32 s19, 0, 0x15c00
	s_lshl_b32 s74, s74, 2
	v_or_b32_e32 v45, s18, v42
; #define LAS __attribute__((address_space(3)))
; __device__ __forceinline__ unsigned f2bf(float f) { unsigned u = __builtin_bit_cast(unsigned, f); return (u + 0x7fffu + ((u >> 16) & 1u)) >> 16; }
; template <bool FULL, bool STORE = true>
; __device__ __forceinline__ void hg_item(const Prm& P, LAS unsigned char* lds, int item, int wave) {
;     ...
;     HG_LOADS(0);
;     ...
;             if (wave < 3) { const int tb = wave ? 1 : 0, sb = wave == 2 ? 1 : 0; f32x16 sc;
; #pragma unroll
;                 for (int r = 0; r < 16; ++r) sc[r] = 0.f;
; #pragma unroll
;                 for (int ks = 0; ks < 8; ++ks) { const bf16x8 a = *(const LAS bf16x8*)(lds + HL_QM + (tb * 32 + l31) * 272 + ks * 32 + lh * 16), bb = *(const LAS bf16x8*)(lds + HL_KM + (sb * 32 + l31) * 272 + ks * 32 + lh * 16);
;                     sc = __builtin_amdgcn_mfma_f32_32x32x16_bf16(a, bb, sc, 0, 0, 0); }
; #pragma unroll
;                 for (int r = 0; r < 16; ++r) { const int t = tb * 32 + (r & 3) + 8 * (r >> 2) + 4 * lh, s = sb * 32 + l31; *(LAS bf16_t*)(lds + HL_PP + t * 144 + s * 2) = (bf16_t)f2bf(s <= t ? sc[r] : 0.f); }
	s_add_i32 s18, 0, 0x11400
	v_mov_b32_e32 v40, s18
	v_add_u32_e32 v57, s18, v128
	v_readlane_b32 s18, v255, 34
	v_mov_b32_e32 v46, s19
	v_add_u32_e32 v74, s59, v34
	v_readlane_b32 s19, v255, 33
	v_or_b32_e32 v95, s18, v42
	v_or_b32_e32 v221, s97, v42
	v_mul_u32_u24_e32 v222, s72, v221
	v_add_lshl_u32 v223, v34, s18, 1
	v_add3_u32 v222, v222, v223, s73
	v_add_u32_e32 v221, s97, v221
	v_subrev_u32_e32 v221, s18, v221
	s_add_u32 vcc_lo, s82, s74
	v_mad_u32_u24 v40, v45, s72, v40
	v_mad_u32_u24 v45, v45, s3, v46
	v_lshl_add_u32 v46, v42, 2, s19
	v_readlane_b32 s19, v255, 29
	v_cmp_lt_i32_e64 s[46:47], v221, v96
	v_add_u32_e32 v96, s48, v34
	v_add_u32_e32 v34, s50, v34
	v_mul_lo_u32 v104, v74, s94
	v_lshlrev_b32_e32 v74, 2, v94
	s_addc_u32 vcc_hi, s83, 0
	v_or_b32_e32 v44, s59, v42
	v_or_b32_e32 v56, s19, v42
	v_mad_u32_u24 v60, v95, s3, 0
	v_lshl_add_u32 v42, v95, 1, s73
	v_cmp_lt_i32_e64 s[18:19], v221, v61
	v_cmp_lt_i32_e64 s[20:21], v221, v62
	v_cmp_lt_i32_e64 s[22:23], v221, v63
	v_cmp_lt_i32_e64 s[24:25], v221, v64
	v_cmp_lt_i32_e64 s[26:27], v221, v65
	v_cmp_lt_i32_e64 s[28:29], v221, v66
	v_cmp_lt_i32_e64 s[30:31], v221, v67
	v_cmp_lt_i32_e64 s[34:35], v221, v68
	v_cmp_lt_i32_e64 s[36:37], v221, v69
	v_cmp_lt_i32_e64 s[38:39], v221, v70
	v_cmp_lt_i32_e64 s[40:41], v221, v71
	v_cmp_lt_i32_e64 s[42:43], v221, v72
	v_cmp_lt_i32_e64 s[44:45], v221, v73
	v_cmp_lt_i32_e64 s[48:49], v221, v96
	v_cmp_lt_i32_e64 s[50:51], v221, v34
	v_lshl_add_u64 v[94:95], vcc, 0, v[74:75]
	s_lshl_b64 vcc, s[84:85], 24
	s_or_b32 vcc_lo, vcc_lo, s33
	v_readlane_b32 s33, v255, 55
	s_add_u32 s33, s33, s52
	s_addc_u32 s53, s90, s53
	v_lshlrev_b64 v[38:39], 11, v[38:39]
	v_and_b32_e32 v32, 7, v32
	s_add_u32 s52, s33, s87
	v_lshl_add_u64 v[38:39], vcc, 0, v[38:39]
	v_lshlrev_b32_e32 v32, 5, v32
	s_addc_u32 s53, s53, 0
	s_or_b32 s33, vcc_lo, s86
	v_mul_lo_u32 v43, v44, s72
	v_mul_lo_u32 v44, v44, s3
	v_mul_lo_u32 v56, v56, s72
	v_mul_lo_u32 v105, v34, s72
	v_mul_u32_u24_e32 v34, 0x90, v33
	v_or3_b32 v38, v38, s86, v32
	v_mov_b32_e32 v32, s33
	v_mov_b32_e32 v33, vcc_hi
	v_add_u32_e32 v43, s73, v43
	v_add_u32_e32 v44, 0, v44
	v_add_u32_e32 v56, 0, v56
	v_mul_lo_u32 v61, v61, s72
	v_mul_lo_u32 v62, v62, s72
	v_mul_lo_u32 v63, v63, s72
	v_mul_lo_u32 v64, v64, s72
	v_mul_lo_u32 v65, v65, s72
	v_mul_lo_u32 v66, v66, s72
	v_mul_lo_u32 v67, v67, s72
	v_mul_lo_u32 v68, v68, s72
	v_mul_lo_u32 v69, v69, s72
	v_mul_lo_u32 v70, v70, s72
	v_mul_lo_u32 v71, v71, s72
	v_mul_lo_u32 v72, v72, s72
	v_mul_lo_u32 v73, v73, s72
	v_mul_lo_u32 v103, v96, s72
	v_lshl_add_u64 v[32:33], v[36:37], 1, v[32:33]
	v_readlane_b32 s33, v255, 51
	v_lshl_add_u64 v[96:97], s[92:93], 0, v[38:39]
	s_lshl_b64 s[84:85], s[52:53], 10
	v_lshl_add_u64 v[98:99], s[78:79], 0, v[32:33]
	v_lshl_add_u64 v[100:101], s[80:81], 0, v[32:33]
	s_mov_b64 s[86:87], 0
	v_add_u32_e32 v132, s33, v47
	v_add_u32_e32 v134, v60, v128
	v_add_u32_e32 v135, v42, v61
	v_add_u32_e32 v136, v42, v62
	v_add_u32_e32 v137, v42, v63
	v_add_u32_e32 v138, v42, v64
	v_add_u32_e32 v139, v42, v65
	v_add_u32_e32 v140, v42, v66
	v_add_u32_e32 v141, v42, v67
	v_add_u32_e32 v142, v42, v68
	v_add_u32_e32 v143, v42, v69
	v_add_u32_e32 v144, v42, v70
	v_add_u32_e32 v145, v42, v71
	v_add_u32_e32 v146, v42, v72
	v_add_u32_e32 v147, v42, v73
	v_add_u32_e32 v148, v42, v102
	v_add_u32_e32 v149, v42, v103
	v_add_u32_e32 v150, v42, v105
	v_add_u32_e32 v151, v44, v128
	v_add_u32_e32 v152, v45, v128
	v_add_u32_e32 v153, v46, v104
	v_add_u32_e32 v154, v56, v128
	v_add_u32_e32 v155, v57, v34
	v_add_u32_e32 v157, v58, v74
	v_add_u32_e32 v158, v43, v128
	v_add_u32_e32 v159, v40, v128
	global_load_dwordx4 v[224:227], v[94:95], off offset:48
	global_load_dwordx4 v[228:231], v[94:95], off offset:32
	global_load_dwordx4 v[232:235], v[94:95], off offset:16
	global_load_dwordx4 v[236:239], v[94:95], off
	s_waitcnt vmcnt(8)
	v_cvt_f32_f16_e32 v78, v240
	v_cvt_f32_f16_sdwa v79, v240 dst_sel:DWORD dst_unused:UNUSED_PAD src0_sel:WORD_1
	v_cvt_f32_f16_e32 v80, v241
	v_cvt_f32_f16_sdwa v81, v241 dst_sel:DWORD dst_unused:UNUSED_PAD src0_sel:WORD_1
	v_cvt_f32_f16_e32 v82, v242
	v_cvt_f32_f16_sdwa v83, v242 dst_sel:DWORD dst_unused:UNUSED_PAD src0_sel:WORD_1
	v_cvt_f32_f16_e32 v84, v243
	v_cvt_f32_f16_sdwa v85, v243 dst_sel:DWORD dst_unused:UNUSED_PAD src0_sel:WORD_1
	v_cvt_f32_f16_e32 v86, v244
	v_cvt_f32_f16_sdwa v87, v244 dst_sel:DWORD dst_unused:UNUSED_PAD src0_sel:WORD_1
	v_cvt_f32_f16_e32 v88, v245
	v_cvt_f32_f16_sdwa v89, v245 dst_sel:DWORD dst_unused:UNUSED_PAD src0_sel:WORD_1
	v_cvt_f32_f16_e32 v90, v246
	v_cvt_f32_f16_sdwa v91, v246 dst_sel:DWORD dst_unused:UNUSED_PAD src0_sel:WORD_1
	v_cvt_f32_f16_e32 v92, v247
	v_cvt_f32_f16_sdwa v93, v247 dst_sel:DWORD dst_unused:UNUSED_PAD src0_sel:WORD_1
	s_branch .LBB0_840
; #define LAS __attribute__((address_space(3)))
; template <bool FULL, bool STORE = true>
; __device__ __forceinline__ void hg_item(const Prm& P, LAS unsigned char* lds, int item, int wave) {
;     ...
;                 for (int ks = 0; ks < 4; ++ks) { if (ks < 2 || tb) { const bf16x8 a = *(const LAS bf16x8*)(lds + HL_PP + (tb * 32 + l31) * 144 + ks * 32 + lh * 16), bb = *(const LAS bf16x8*)(lds + HL_IVT + (vb * 32 + l31) * 144 + ks * 32 + lh * 16);
;                         o = __builtin_amdgcn_mfma_f32_32x32x16_bf16(a, bb, o, 0, 0, 0); } }
; #pragma unroll
;                 for (int ks = 0; ks < 8; ++ks) { const bf16x8 a = *(const LAS bf16x8*)(lds + HL_QD + (tb * 32 + l31) * 272 + ks * 32 + lh * 16), bb = *(const LAS bf16x8*)(lds + HL_ST + (vb * 32 + l31) * 272 + ks * 32 + lh * 16);
;                     o = __builtin_amdgcn_mfma_f32_32x32x16_bf16(a, bb, o, 0, 0, 0); }
; #pragma unroll
;                 for (int r = 0; r < 16; ++r) { const int t = tb * 32 + (r & 3) + 8 * (r >> 2) + 4 * lh; *(LAS float*)(lds + HL_OS + t * 528 + (vb * 32 + l31) * 4) = o[r]; }
;             }
;         }
; #pragma unroll
;         for (int g4 = 0; g4 < 4; ++g4) { const f32x4 d = *(const LAS f32x4*)(lds + HL_DC + (kb * 32 + 8 * g4 + 4 * lh) * 4);
; #pragma unroll
;             for (int i = 0; i < 2; ++i)
; #pragma unroll
;                 for (int j = 0; j < 4; ++j) S[i][4 * g4 + j] *= d[j]; }
; #pragma unroll
;         for (int ks = 0; ks < 4; ++ks) { const bf16x8 a = *(const LAS bf16x8*)(lds + HL_KDT + (kb * 32 + l31) * 144 + ks * 32 + lh * 16);
; #pragma unroll
;             for (int i = 0; i < 2; ++i) { const bf16x8 bb = *(const LAS bf16x8*)(lds + HL_IVT + ((vb0 + i) * 32 + l31) * 144 + ks * 32 + lh * 16); S[i] = __builtin_amdgcn_mfma_f32_32x32x16_bf16(a, bb, S[i], 0, 0, 0); } }
.LBB0_839:
	s_mov_b32 s33, 0x800000
	s_add_u32 s86, s86, 0x20000
	s_addc_u32 s87, s87, 0
	v_lshlrev_b32_e32 v104, 16, v52
	v_and_b32_e32 v105, 0xffff0000, v52
	v_lshlrev_b32_e32 v52, 16, v53
	v_and_b32_e32 v53, 0xffff0000, v53
	s_add_u32 s84, s84, 0x10000
	s_addc_u32 s85, s85, 0
	s_cmp_lg_u32 s86, 0x200000
	s_waitcnt lgkmcnt(6)
	v_mfma_f32_32x32x16_bf16 v[32:47], v[172:175], v[176:179], v[32:47]
	ds_read_b128 v[172:175], v151 offset:34944
	ds_read_b128 v[176:179], v152 offset:128
	s_waitcnt lgkmcnt(6)
	v_mfma_f32_32x32x16_bf16 v[32:47], v[180:183], v[184:187], v[32:47]
	ds_read_b128 v[180:183], v151 offset:34976
	ds_read_b128 v[184:187], v152 offset:160
	s_waitcnt lgkmcnt(6)
	v_mfma_f32_32x32x16_bf16 v[32:47], v[188:191], v[192:195], v[32:47]
	ds_read_b128 v[188:191], v151 offset:35008
	ds_read_b128 v[192:195], v152 offset:192
	s_waitcnt lgkmcnt(6)
	v_mfma_f32_32x32x16_bf16 v[32:47], v[196:199], v[200:203], v[32:47]
	ds_read_b128 v[196:199], v151 offset:35040
	ds_read_b128 v[200:203], v152 offset:224
	s_waitcnt lgkmcnt(6)
	v_mfma_f32_32x32x16_bf16 v[32:47], v[172:175], v[176:179], v[32:47]
	s_waitcnt lgkmcnt(4)
	v_mfma_f32_32x32x16_bf16 v[32:47], v[180:183], v[184:187], v[32:47]
	s_waitcnt lgkmcnt(2)
	v_mfma_f32_32x32x16_bf16 v[32:47], v[188:191], v[192:195], v[32:47]
	s_waitcnt lgkmcnt(0)
	v_mfma_f32_32x32x16_bf16 v[32:47], v[196:199], v[200:203], v[32:47]
	s_nop 11
	ds_write2_b32 v153, v32, v33 offset1:132
	v_add_u32_e32 v32, 0x400, v153
	ds_write2_b32 v32, v34, v35 offset0:8 offset1:140
	v_add_u32_e32 v32, 0x1000, v153
	ds_write2_b32 v32, v36, v37 offset0:32 offset1:164
	v_add_u32_e32 v32, 0x1400, v153
	ds_write2_b32 v32, v38, v39 offset0:40 offset1:172
	v_add_u32_e32 v32, 0x2000, v153
	ds_write2_b32 v32, v40, v41 offset0:64 offset1:196
	v_add_u32_e32 v32, 0x2400, v153
	ds_write2_b32 v32, v42, v43 offset0:72 offset1:204
	v_add_u32_e32 v32, 0x3000, v153
	ds_write2_b32 v32, v44, v45 offset0:96 offset1:228
	v_add_u32_e32 v32, 0x3400, v153
	ds_write2_b32 v32, v46, v47 offset0:104 offset1:236
	v_add_u32_e32 v220, s96, v128
	ds_read_b128 v[32:35], v220
	ds_read_b128 v[36:39], v220 offset:32
	ds_read_b128 v[40:43], v220 offset:64
	ds_read_b128 v[44:47], v220 offset:96
	ds_read_b128 v[172:175], v154 offset:52224
	ds_read_b128 v[188:191], v155
	ds_read_b128 v[204:207], v155 offset:4608
	ds_read_b128 v[176:179], v154 offset:52256
	ds_read_b128 v[192:195], v155 offset:32
	ds_read_b128 v[208:211], v155 offset:4640
	s_waitcnt lgkmcnt(9)
	v_pk_mul_f32 v[0:1], v[0:1], v[32:33]
	v_pk_mul_f32 v[2:3], v[2:3], v[34:35]
	v_pk_mul_f32 v[16:17], v[16:17], v[32:33]
	v_pk_mul_f32 v[18:19], v[18:19], v[34:35]
	s_waitcnt lgkmcnt(8)
	v_pk_mul_f32 v[4:5], v[4:5], v[36:37]
	v_pk_mul_f32 v[6:7], v[6:7], v[38:39]
	v_pk_mul_f32 v[20:21], v[20:21], v[36:37]
	v_pk_mul_f32 v[22:23], v[22:23], v[38:39]
	s_waitcnt lgkmcnt(7)
	v_pk_mul_f32 v[8:9], v[8:9], v[40:41]
	v_pk_mul_f32 v[10:11], v[10:11], v[42:43]
	v_pk_mul_f32 v[24:25], v[24:25], v[40:41]
	v_pk_mul_f32 v[26:27], v[26:27], v[42:43]
	s_waitcnt lgkmcnt(6)
	v_pk_mul_f32 v[12:13], v[12:13], v[44:45]
	v_pk_mul_f32 v[14:15], v[14:15], v[46:47]
	v_pk_mul_f32 v[28:29], v[28:29], v[44:45]
	v_pk_mul_f32 v[30:31], v[30:31], v[46:47]
	ds_read_b128 v[180:183], v154 offset:52288
	ds_read_b128 v[196:199], v155 offset:64
	ds_read_b128 v[212:215], v155 offset:4672
	ds_read_b128 v[184:187], v154 offset:52320
	ds_read_b128 v[200:203], v155 offset:96
	ds_read_b128 v[216:219], v155 offset:4704
	s_waitcnt lgkmcnt(10)
	v_mfma_f32_32x32x16_bf16 v[0:15], v[172:175], v[188:191], v[0:15]
	s_waitcnt lgkmcnt(9)
	v_mfma_f32_32x32x16_bf16 v[16:31], v[172:175], v[204:207], v[16:31]
	s_waitcnt lgkmcnt(7)
	v_mfma_f32_32x32x16_bf16 v[0:15], v[176:179], v[192:195], v[0:15]
	s_waitcnt lgkmcnt(6)
	v_mfma_f32_32x32x16_bf16 v[16:31], v[176:179], v[208:211], v[16:31]
	s_waitcnt lgkmcnt(4)
	v_mfma_f32_32x32x16_bf16 v[0:15], v[180:183], v[196:199], v[0:15]
	s_waitcnt lgkmcnt(3)
	v_mfma_f32_32x32x16_bf16 v[16:31], v[180:183], v[212:215], v[16:31]
	s_waitcnt lgkmcnt(1)
	v_mfma_f32_32x32x16_bf16 v[0:15], v[184:187], v[200:203], v[0:15]
	s_waitcnt lgkmcnt(0)
	s_barrier
; #define LAS __attribute__((address_space(3)))
; __device__ __forceinline__ unsigned pk2(float lo, float hi) { typedef float f2v __attribute__((ext_vector_type(2))); typedef __bf16 b2v __attribute__((ext_vector_type(2))); const f2v v = {lo, hi}; const b2v b = __builtin_convertvector(v, b2v); return __builtin_bit_cast(unsigned, b); }
; __device__ __forceinline__ u32x4 pack8(const float (&f)[8]) { u32x4 w; w.x = pk2(f[0], f[1]); w.y = pk2(f[2], f[3]); w.z = pk2(f[4], f[5]); w.w = pk2(f[6], f[7]); return w; }
; template <bool FULL, bool STORE = true>
; __device__ __forceinline__ void hg_item(const Prm& P, LAS unsigned char* lds, int item, int wave) {
;     ...
;         if (FULL) {
;             __syncthreads();
; #pragma unroll
;             for (int i = 0; i < 2; ++i)
; #pragma unroll
;                 for (int g4 = 0; g4 < 4; ++g4) { u32x2 w; w.x = pk2(S[i][4 * g4], S[i][4 * g4 + 1]); w.y = pk2(S[i][4 * g4 + 2], S[i][4 * g4 + 3]);
;                     *(LAS u32x2*)(lds + HL_ST + ((vb0 + i) * 32 + l31) * 272 + (kb * 32 + 8 * g4 + 4 * lh) * 2) = w; }
;             { const int t = tid >> 3, vs = (tid & 7) * 16; float o[16]; float ss = 0.f;
; #pragma unroll
;                 for (int q4 = 0; q4 < 4; ++q4) { const f32x4 x4 = *(const LAS f32x4*)(lds + HL_OS + t * 528 + (vs + 4 * q4) * 4);
; #pragma unroll
;                     for (int j = 0; j < 4; ++j) { o[4 * q4 + j] = x4[j]; ss += x4[j] * x4[j]; } }
;                 ss += __shfl_xor(ss, 1); ss += __shfl_xor(ss, 2); ss += __shfl_xor(ss, 4);
;                 const float r = rsqrtf(ss * (1.0f / 128.0f) + EPS);
;                 const size_t oo = (row0 + t) * 1024 + h * 128 + vs; const float* gn = P.in[I_HGNG] + h * 128 + vs;
;                 float g0[8], g1[8]; unpack8(gcur0, g0); unpack8(gcur1, g1);
;                 float w0[8], w1[8];
; #pragma unroll
;                 for (int j = 0; j < 8; ++j) { w0[j] = o[j] * r * gn[j] * g0[j]; w1[j] = o[8 + j] * r * gn[8 + j] * g1[j]; }
;                 if (STORE) { *(u32x4*)(AHG + oo) = pack8(w0); *(u32x4*)(AHG + oo + 8) = pack8(w1); }
	v_mfma_f32_32x32x16_bf16 v[16:31], v[184:187], v[216:219], v[16:31]
	s_nop 8
	v_cvt_pk_bf16_f32 v32, v0, v1
	v_cvt_pk_bf16_f32 v33, v2, v3
	v_cvt_pk_bf16_f32 v34, v4, v5
	v_cvt_pk_bf16_f32 v35, v6, v7
	ds_write2_b64 v156, v[32:33], v[34:35] offset1:2
	v_cvt_pk_bf16_f32 v32, v8, v9
	v_cvt_pk_bf16_f32 v33, v10, v11
	v_cvt_pk_bf16_f32 v34, v12, v13
	v_cvt_pk_bf16_f32 v35, v14, v15
	ds_write2_b64 v156, v[32:33], v[34:35] offset0:4 offset1:6
	v_cvt_pk_bf16_f32 v32, v16, v17
	v_cvt_pk_bf16_f32 v33, v18, v19
	v_cvt_pk_bf16_f32 v34, v20, v21
	v_cvt_pk_bf16_f32 v35, v22, v23
	v_add_u32_e32 v36, 0x2000, v156
	ds_write2_b64 v36, v[32:33], v[34:35] offset0:64 offset1:66
	v_cvt_pk_bf16_f32 v32, v24, v25
	v_cvt_pk_bf16_f32 v33, v26, v27
	v_cvt_pk_bf16_f32 v34, v28, v29
	v_cvt_pk_bf16_f32 v35, v30, v31
	ds_write2_b64 v36, v[32:33], v[34:35] offset0:68 offset1:70
	ds_read_b128 v[66:69], v157
	ds_read_b128 v[36:39], v157 offset:16
	ds_read_b128 v[44:47], v157 offset:32
	ds_read_b128 v[32:35], v157 offset:48
	s_waitcnt lgkmcnt(3)
	v_mul_f32_e32 v64, v67, v67
	v_fmac_f32_e32 v64, v66, v66
	v_fmac_f32_e32 v64, v68, v68
	v_fmac_f32_e32 v64, v69, v69
	s_waitcnt lgkmcnt(2)
	v_fmac_f32_e32 v64, v36, v36
	v_fmac_f32_e32 v64, v37, v37
	v_fmac_f32_e32 v64, v38, v38
	v_fmac_f32_e32 v64, v39, v39
	s_waitcnt lgkmcnt(1)
	v_pk_mul_f32 v[42:43], v[44:45], v[44:45]
	v_pk_mul_f32 v[40:41], v[46:47], v[46:47]
	v_add_f32_e32 v42, v42, v64
	v_add_f32_e32 v42, v43, v42
	v_add_f32_e32 v40, v40, v42
	v_add_f32_e32 v64, v41, v40
	s_waitcnt lgkmcnt(0)
	v_pk_mul_f32 v[42:43], v[32:33], v[32:33]
	v_pk_mul_f32 v[40:41], v[34:35], v[34:35]
	v_add_f32_e32 v42, v42, v64
	v_add_f32_e32 v42, v43, v42
	v_add_f32_e32 v40, v40, v42
	v_add_f32_e32 v40, v41, v40
	s_nop 1
	v_add_f32_dpp v40, v40, v40 quad_perm:[1,0,3,2] row_mask:0xf bank_mask:0xf
	s_nop 1
	v_add_f32_dpp v40, v40, v40 quad_perm:[2,3,0,1] row_mask:0xf bank_mask:0xf
	s_nop 1
	v_add_f32_dpp v40, v40, v40 row_half_mirror row_mask:0xf bank_mask:0xf
	v_fmamk_f32 v40, v40, 0x3c000000, v109
	v_cmp_gt_f32_e32 vcc, s33, v40
	v_mul_f32_e32 v41, 0x4b800000, v40
	s_mov_b32 s33, 0x7400000
	v_cndmask_b32_e32 v40, v40, v41, vcc
	v_rsq_f32_e32 v40, v40
	s_nop 0
	v_mul_f32_e32 v41, 0x45800000, v40
	v_cndmask_b32_e32 v74, v40, v41, vcc
	v_pk_mul_f32 v[106:107], v[66:67], v[74:75] op_sel_hi:[1,0]
	v_pk_mul_f32 v[46:47], v[46:47], v[74:75] op_sel_hi:[1,0]
	v_pk_mul_f32 v[36:37], v[36:37], v[74:75] op_sel_hi:[1,0]
	v_pk_mul_f32 v[32:33], v[32:33], v[74:75] op_sel_hi:[1,0]
	v_pk_mul_f32 v[44:45], v[44:45], v[74:75] op_sel_hi:[1,0]
	v_pk_mul_f32 v[38:39], v[38:39], v[74:75] op_sel_hi:[1,0]
	v_pk_mul_f32 v[34:35], v[34:35], v[74:75] op_sel_hi:[1,0]
	s_waitcnt vmcnt(0)
	v_pk_mul_f32 v[32:33], v[224:225], v[32:33]
	v_pk_mul_f32 v[46:47], v[230:231], v[46:47]
	v_pk_mul_f32 v[36:37], v[232:233], v[36:37]
	v_pk_mul_f32 v[106:107], v[236:237], v[106:107]
	v_pk_mul_f32 v[44:45], v[228:229], v[44:45]
	v_pk_mul_f32 v[104:105], v[106:107], v[104:105]
	v_lshlrev_b32_e32 v106, 16, v48
	v_and_b32_e32 v107, 0xffff0000, v48
	v_lshlrev_b32_e32 v48, 16, v49
	v_and_b32_e32 v49, 0xffff0000, v49
	v_pk_mul_f32 v[46:47], v[46:47], v[48:49]
	v_lshlrev_b32_e32 v48, 16, v54
	v_and_b32_e32 v49, 0xffff0000, v54
	v_pk_mul_f32 v[36:37], v[36:37], v[48:49]
	v_lshlrev_b32_e32 v48, 16, v50
	v_and_b32_e32 v49, 0xffff0000, v50
	v_pk_mul_f32 v[64:65], v[68:69], v[74:75] op_sel_hi:[1,0]
	v_pk_mul_f32 v[40:41], v[32:33], v[48:49]
	v_lshlrev_b32_e32 v32, 16, v55
	v_and_b32_e32 v33, 0xffff0000, v55
	v_pk_mul_f32 v[38:39], v[234:235], v[38:39]
	v_pk_mul_f32 v[64:65], v[238:239], v[64:65]
	v_pk_mul_f32 v[38:39], v[38:39], v[32:33]
	v_lshlrev_b32_e32 v32, 16, v51
	v_and_b32_e32 v33, 0xffff0000, v51
	v_pk_mul_f32 v[34:35], v[226:227], v[34:35]
	v_pk_mul_f32 v[52:53], v[64:65], v[52:53]
	v_pk_mul_f32 v[42:43], v[34:35], v[32:33]
	v_cvt_pk_bf16_f32 v34, v36, v37
	v_add_co_u32_e32 v36, vcc, s33, v102
	v_pk_mul_f32 v[44:45], v[44:45], v[106:107]
	v_cvt_pk_bf16_f32 v32, v104, v105
	v_cvt_pk_bf16_f32 v33, v52, v53
	v_cvt_pk_bf16_f32 v35, v38, v39
	v_addc_co_u32_e32 v37, vcc, 0, v103, vcc
	v_mov_b64_e32 v[52:53], v[56:57]
	v_mov_b64_e32 v[48:49], v[60:61]
	global_store_dwordx4 v[36:37], v[32:35], off
	v_mov_b64_e32 v[54:55], v[58:59]
	v_mov_b64_e32 v[50:51], v[62:63]
	v_cvt_pk_bf16_f32 v32, v44, v45
	v_cvt_pk_bf16_f32 v33, v46, v47
	v_cvt_pk_bf16_f32 v34, v40, v41
	v_cvt_pk_bf16_f32 v35, v42, v43
	global_store_dwordx4 v[36:37], v[32:35], off offset:16
	v_cvt_f32_f16_e32 v78, v240
	v_cvt_f32_f16_sdwa v79, v240 dst_sel:DWORD dst_unused:UNUSED_PAD src0_sel:WORD_1
	v_cvt_f32_f16_e32 v80, v241
	v_cvt_f32_f16_sdwa v81, v241 dst_sel:DWORD dst_unused:UNUSED_PAD src0_sel:WORD_1
	v_cvt_f32_f16_e32 v82, v242
	v_cvt_f32_f16_sdwa v83, v242 dst_sel:DWORD dst_unused:UNUSED_PAD src0_sel:WORD_1
	v_cvt_f32_f16_e32 v84, v243
	v_cvt_f32_f16_sdwa v85, v243 dst_sel:DWORD dst_unused:UNUSED_PAD src0_sel:WORD_1
	v_cvt_f32_f16_e32 v86, v244
	v_cvt_f32_f16_sdwa v87, v244 dst_sel:DWORD dst_unused:UNUSED_PAD src0_sel:WORD_1
	v_cvt_f32_f16_e32 v88, v245
	v_cvt_f32_f16_sdwa v89, v245 dst_sel:DWORD dst_unused:UNUSED_PAD src0_sel:WORD_1
	v_cvt_f32_f16_e32 v90, v246
	v_cvt_f32_f16_sdwa v91, v246 dst_sel:DWORD dst_unused:UNUSED_PAD src0_sel:WORD_1
	v_cvt_f32_f16_e32 v92, v247
	v_cvt_f32_f16_sdwa v93, v247 dst_sel:DWORD dst_unused:UNUSED_PAD src0_sel:WORD_1
	s_cbranch_scc0 .LBB0_821

; #define LAS __attribute__((address_space(3)))
; __device__ __forceinline__ unsigned f2bf(float f) { unsigned u = __builtin_bit_cast(unsigned, f); return (u + 0x7fffu + ((u >> 16) & 1u)) >> 16; }
; template <bool FULL, bool STORE = true>
; __device__ __forceinline__ void hg_item(const Prm& P, LAS unsigned char* lds, int item, int wave) {
;     ...
;         if (FULL) {
;             if (wave < 3) { const int tb = wave ? 1 : 0, sb = wave == 2 ? 1 : 0; f32x16 sc;
; #pragma unroll
;                 for (int r = 0; r < 16; ++r) sc[r] = 0.f;
; #pragma unroll
;                 for (int ks = 0; ks < 8; ++ks) { const bf16x8 a = *(const LAS bf16x8*)(lds + HL_QM + (tb * 32 + l31) * 272 + ks * 32 + lh * 16), bb = *(const LAS bf16x8*)(lds + HL_KM + (sb * 32 + l31) * 272 + ks * 32 + lh * 16);
;                     sc = __builtin_amdgcn_mfma_f32_32x32x16_bf16(a, bb, sc, 0, 0, 0); }
; #pragma unroll
;                 for (int r = 0; r < 16; ++r) { const int t = tb * 32 + (r & 3) + 8 * (r >> 2) + 4 * lh, s = sb * 32 + l31; *(LAS bf16_t*)(lds + HL_PP + t * 144 + s * 2) = (bf16_t)f2bf(s <= t ? sc[r] : 0.f); }
;             }
.LBB0_844:
	s_andn2_b64 vcc, exec, s[76:77]
	s_waitcnt lgkmcnt(0)
	s_barrier
	s_cbranch_vccnz .LBB0_846
	ds_read_b128 v[172:175], v133
	ds_read_b128 v[176:179], v134 offset:17408
	ds_read_b128 v[180:183], v133 offset:32
	ds_read_b128 v[184:187], v134 offset:17440
	ds_read_b128 v[188:191], v133 offset:64
	ds_read_b128 v[192:195], v134 offset:17472
	ds_read_b128 v[196:199], v133 offset:96
	ds_read_b128 v[200:203], v134 offset:17504
	s_waitcnt lgkmcnt(6)
	v_mfma_f32_32x32x16_bf16 v[32:47], v[176:179], v[172:175], 0
	ds_read_b128 v[172:175], v133 offset:128
	ds_read_b128 v[176:179], v134 offset:17536
	s_waitcnt lgkmcnt(6)
	v_mfma_f32_32x32x16_bf16 v[32:47], v[184:187], v[180:183], v[32:47]
	ds_read_b128 v[180:183], v133 offset:160
	ds_read_b128 v[184:187], v134 offset:17568
	s_waitcnt lgkmcnt(6)
	v_mfma_f32_32x32x16_bf16 v[32:47], v[192:195], v[188:191], v[32:47]
	ds_read_b128 v[188:191], v133 offset:192
	ds_read_b128 v[192:195], v134 offset:17600
	s_waitcnt lgkmcnt(6)
	v_mfma_f32_32x32x16_bf16 v[32:47], v[200:203], v[196:199], v[32:47]
	ds_read_b128 v[196:199], v133 offset:224
	ds_read_b128 v[200:203], v134 offset:17632
	s_waitcnt lgkmcnt(6)
	v_mfma_f32_32x32x16_bf16 v[32:47], v[176:179], v[172:175], v[32:47]
	s_waitcnt lgkmcnt(4)
	v_mfma_f32_32x32x16_bf16 v[32:47], v[184:187], v[180:183], v[32:47]
	s_waitcnt lgkmcnt(2)
	v_mfma_f32_32x32x16_bf16 v[32:47], v[192:195], v[188:191], v[32:47]
	s_waitcnt lgkmcnt(0)
	v_mfma_f32_32x32x16_bf16 v[32:47], v[200:203], v[196:199], v[32:47]
	s_nop 11
	v_cndmask_b32_e64 v32, v32, 0, s[18:19]
	v_cndmask_b32_e64 v33, v33, 0, s[20:21]
	v_cndmask_b32_e64 v34, v34, 0, s[22:23]
	v_cndmask_b32_e64 v35, v35, 0, s[24:25]
	v_cndmask_b32_e64 v36, v36, 0, s[26:27]
	v_cndmask_b32_e64 v37, v37, 0, s[28:29]
	v_cndmask_b32_e64 v38, v38, 0, s[30:31]
	v_cndmask_b32_e64 v39, v39, 0, s[34:35]
	v_cndmask_b32_e64 v40, v40, 0, s[36:37]
	v_cndmask_b32_e64 v41, v41, 0, s[38:39]
	v_cndmask_b32_e64 v42, v42, 0, s[40:41]
	v_cndmask_b32_e64 v43, v43, 0, s[42:43]
	v_cndmask_b32_e64 v44, v44, 0, s[44:45]
	v_cndmask_b32_e64 v45, v45, 0, s[46:47]
	v_cndmask_b32_e64 v46, v46, 0, s[48:49]
	v_cndmask_b32_e64 v47, v47, 0, s[50:51]
	v_cvt_pk_bf16_f32 v64, v32, v33
	v_cvt_pk_bf16_f32 v65, v34, v35
	ds_write_b64 v222, v[64:65]
	v_cvt_pk_bf16_f32 v66, v36, v37
	v_cvt_pk_bf16_f32 v67, v38, v39
	ds_write_b64 v222, v[66:67] offset:16
	v_cvt_pk_bf16_f32 v68, v40, v41
	v_cvt_pk_bf16_f32 v69, v42, v43
	ds_write_b64 v222, v[68:69] offset:32
	v_cvt_pk_bf16_f32 v70, v44, v45
	v_cvt_pk_bf16_f32 v71, v46, v47
	ds_write_b64 v222, v[70:71] offset:48
